# final-phase loop: keep next-row prefetch loads in flight (waits moved to first use)
# speedup vs baseline: 1.0151x; 1.0005x over previous
.LBB0_859:
	s_or_b64 exec, exec, s[2:3]
	v_lshlrev_b32_e32 v136, 16, v92
	v_and_b32_e32 v137, 0xffff0000, v92
	v_lshlrev_b32_e32 v92, 16, v93
	v_and_b32_e32 v93, 0xffff0000, v93
	v_lshlrev_b32_e32 v138, 16, v88
	v_and_b32_e32 v139, 0xffff0000, v88
	v_lshlrev_b32_e32 v88, 16, v89
	v_and_b32_e32 v89, 0xffff0000, v89
	v_pk_fma_f32 v[88:89], v[100:101], v[92:93], v[88:89]
	v_pk_fma_f32 v[92:93], v[98:99], v[136:137], v[138:139]
	v_lshlrev_b32_e32 v136, 16, v94
	v_and_b32_e32 v137, 0xffff0000, v94
	v_lshlrev_b32_e32 v94, 16, v95
	v_and_b32_e32 v95, 0xffff0000, v95
	v_lshlrev_b32_e32 v138, 16, v90
	v_and_b32_e32 v139, 0xffff0000, v90
	v_lshlrev_b32_e32 v90, 16, v91
	v_and_b32_e32 v91, 0xffff0000, v91
	v_pk_fma_f32 v[90:91], v[104:105], v[94:95], v[90:91]
	v_pk_fma_f32 v[94:95], v[102:103], v[136:137], v[138:139]
	v_lshlrev_b32_e32 v136, 16, v84
	v_and_b32_e32 v137, 0xffff0000, v84
	v_lshlrev_b32_e32 v138, 16, v80
	v_and_b32_e32 v139, 0xffff0000, v80
	v_lshlrev_b32_e32 v140, 16, v81
	v_and_b32_e32 v141, 0xffff0000, v81
	v_pk_fma_f32 v[80:81], v[106:107], v[136:137], v[138:139]
	v_lshlrev_b32_e32 v136, 16, v86
	v_and_b32_e32 v137, 0xffff0000, v86
	v_lshlrev_b32_e32 v86, 16, v87
	v_and_b32_e32 v87, 0xffff0000, v87
	v_lshlrev_b32_e32 v138, 16, v82
	v_and_b32_e32 v139, 0xffff0000, v82
	v_lshlrev_b32_e32 v82, 16, v83
	v_and_b32_e32 v83, 0xffff0000, v83
	v_pk_fma_f32 v[82:83], v[112:113], v[86:87], v[82:83]
	v_pk_fma_f32 v[86:87], v[110:111], v[136:137], v[138:139]
	v_lshlrev_b32_e32 v136, 16, v76
	v_and_b32_e32 v137, 0xffff0000, v76
	v_lshlrev_b32_e32 v76, 16, v77
	v_and_b32_e32 v77, 0xffff0000, v77
	v_lshlrev_b32_e32 v138, 16, v72
	v_and_b32_e32 v139, 0xffff0000, v72
	v_lshlrev_b32_e32 v72, 16, v73
	v_and_b32_e32 v73, 0xffff0000, v73
	v_pk_fma_f32 v[72:73], v[116:117], v[76:77], v[72:73]
	v_pk_fma_f32 v[76:77], v[114:115], v[136:137], v[138:139]
	v_lshlrev_b32_e32 v136, 16, v78
	v_and_b32_e32 v137, 0xffff0000, v78
	v_lshlrev_b32_e32 v78, 16, v79
	v_and_b32_e32 v79, 0xffff0000, v79
	v_lshlrev_b32_e32 v138, 16, v74
	v_and_b32_e32 v139, 0xffff0000, v74
	v_lshlrev_b32_e32 v74, 16, v75
	v_and_b32_e32 v75, 0xffff0000, v75
	v_pk_fma_f32 v[136:137], v[118:119], v[136:137], v[138:139]
	v_pk_fma_f32 v[74:75], v[120:121], v[78:79], v[74:75]
	v_lshlrev_b32_e32 v78, 16, v68
	v_and_b32_e32 v79, 0xffff0000, v68
	v_lshlrev_b32_e32 v68, 16, v69
	v_and_b32_e32 v69, 0xffff0000, v69
	v_lshlrev_b32_e32 v138, 16, v64
	v_and_b32_e32 v139, 0xffff0000, v64
	v_lshlrev_b32_e32 v64, 16, v65
	v_and_b32_e32 v65, 0xffff0000, v65
	v_pk_fma_f32 v[68:69], v[124:125], v[68:69], v[64:65]
	v_pk_fma_f32 v[78:79], v[122:123], v[78:79], v[138:139]
	v_lshlrev_b32_e32 v64, 16, v70
	v_and_b32_e32 v65, 0xffff0000, v70
	v_lshlrev_b32_e32 v70, 16, v71
	v_and_b32_e32 v71, 0xffff0000, v71
	v_lshlrev_b32_e32 v138, 16, v66
	v_and_b32_e32 v139, 0xffff0000, v66
	v_lshlrev_b32_e32 v66, 16, v67
	v_and_b32_e32 v67, 0xffff0000, v67
	v_lshlrev_b32_e32 v84, 16, v85
	v_and_b32_e32 v85, 0xffff0000, v85
	v_pk_fma_f32 v[70:71], v[128:129], v[70:71], v[66:67]
	v_mov_b32_e32 v66, v93
	v_mov_b32_e32 v67, v95
	v_pk_fma_f32 v[84:85], v[108:109], v[84:85], v[140:141]
	v_pk_fma_f32 v[138:139], v[126:127], v[64:65], v[138:139]
	v_mov_b32_e32 v64, v92
	v_mov_b32_e32 v65, v94
	v_pk_mul_f32 v[66:67], v[66:67], v[66:67]
	v_mov_b32_e32 v140, v89
	v_mov_b32_e32 v141, v91
	v_pk_fma_f32 v[64:65], v[64:65], v[64:65], v[66:67]
	v_mov_b32_e32 v66, v88
	v_mov_b32_e32 v67, v90
	v_pk_mul_f32 v[140:141], v[140:141], v[140:141]
	s_and_b64 s[0:1], exec, s[0:1]
	v_pk_fma_f32 v[66:67], v[66:67], v[66:67], v[140:141]
	v_pk_mul_f32 v[140:141], v[80:81], v[80:81]
	v_pk_add_f32 v[64:65], v[64:65], v[66:67]
	v_pk_mul_f32 v[66:67], v[84:85], v[84:85]
	v_pk_add_f32 v[64:65], v[64:65], v[64:65] op_sel_hi:[0,1]
	v_pk_mov_b32 v[142:143], v[140:141], v[66:67] op_sel:[1,0]
	v_mov_b32_e32 v141, v67
	v_mul_f32_e32 v64, v86, v86
	v_pk_add_f32 v[66:67], v[142:143], v[140:141]
	v_pk_fma_f32 v[140:141], v[86:87], v[86:87], v[64:65] op_sel_hi:[1,1,0]
	v_mul_f32_e32 v64, v82, v82
	v_pk_add_f32 v[66:67], v[66:67], v[66:67] op_sel_hi:[0,1]
	v_pk_fma_f32 v[142:143], v[82:83], v[82:83], v[64:65] op_sel_hi:[1,1,0]
	v_mul_f32_e32 v140, v76, v76
	v_mul_f32_e32 v142, v77, v77
	v_mul_f32_e32 v64, v72, v72
	v_mul_f32_e32 v66, v73, v73
	v_pk_add_f32 v[140:141], v[140:141], v[142:143]
	v_pk_add_f32 v[64:65], v[64:65], v[66:67]
	v_pk_mul_f32 v[66:67], v[74:75], v[74:75]
	v_pk_add_f32 v[64:65], v[140:141], v[64:65]
	v_pk_mul_f32 v[140:141], v[136:137], v[136:137]
	v_pk_add_f32 v[64:65], v[64:65], v[64:65] op_sel_hi:[0,1]
	v_pk_mov_b32 v[142:143], v[140:141], v[66:67] op_sel:[1,0]
	v_mov_b32_e32 v141, v67
	v_mul_f32_e32 v64, v78, v78
	v_pk_add_f32 v[66:67], v[142:143], v[140:141]
	v_pk_fma_f32 v[140:141], v[78:79], v[78:79], v[64:65] op_sel_hi:[1,1,0]
	v_mul_f32_e32 v64, v68, v68
	v_pk_add_f32 v[66:67], v[66:67], v[66:67] op_sel_hi:[0,1]
	v_pk_fma_f32 v[142:143], v[68:69], v[68:69], v[64:65] op_sel_hi:[1,1,0]
	v_mul_f32_e32 v140, v138, v138
	v_mul_f32_e32 v142, v139, v139
	v_mul_f32_e32 v66, v70, v70
	v_mul_f32_e32 v64, v71, v71
	v_pk_add_f32 v[140:141], v[140:141], v[142:143]
	v_pk_add_f32 v[64:65], v[66:67], v[64:65]
	s_or_b64 s[6:7], s[0:1], s[6:7]
	v_pk_add_f32 v[64:65], v[140:141], v[64:65]
	v_lshl_add_u64 v[132:133], v[132:133], 0, s[22:23]
	v_add_f32_e32 v64, v64, v65
	s_nop 1
	v_add_f32_dpp v64, v64, v64 quad_perm:[1,0,3,2] row_mask:0xf bank_mask:0xf bound_ctrl:1
	s_nop 1
	v_add_f32_dpp v64, v64, v64 quad_perm:[2,3,0,1] row_mask:0xf bank_mask:0xf bound_ctrl:1
	s_nop 1
	v_add_f32_dpp v64, v64, v64 row_half_mirror row_mask:0xf bank_mask:0xf bound_ctrl:1
	s_nop 1
	v_add_f32_dpp v64, v64, v64 row_mirror row_mask:0xf bank_mask:0xf bound_ctrl:1
	s_nop 0
	v_readlane_b32 s10, v64, 16
	v_readlane_b32 s11, v64, 48
	v_readlane_b32 s2, v64, 0
	v_readlane_b32 s3, v64, 32
	v_mov_b32_e32 v64, s10
	v_mov_b32_e32 v65, s11
	v_pk_add_f32 v[64:65], s[2:3], v[64:65]
	s_nop 0
	v_add_f32_e32 v64, v64, v65
	v_fmamk_f32 v64, v64, 0x3a000000, v97
	v_mul_f32_e32 v65, 0x4f800000, v64
	v_cmp_gt_f32_e32 vcc, s9, v64
	s_nop 1
	v_cndmask_b32_e32 v64, v64, v65, vcc
	v_sqrt_f32_e32 v65, v64
	s_nop 0
	v_add_u32_e32 v66, -1, v65
	v_fma_f32 v67, -v66, v65, v64
	v_cmp_ge_f32_e64 s[2:3], 0, v67
	v_add_u32_e32 v67, 1, v65
	s_nop 0
	v_cndmask_b32_e64 v66, v65, v66, s[2:3]
	v_fma_f32 v65, -v67, v65, v64
	v_cmp_lt_f32_e64 s[2:3], 0, v65
	s_nop 1
	v_cndmask_b32_e64 v65, v66, v67, s[2:3]
	v_mul_f32_e32 v66, 0x37800000, v65
	v_cndmask_b32_e32 v65, v65, v66, vcc
	v_cmp_class_f32_e32 vcc, v64, v134
	s_nop 1
	v_cndmask_b32_e32 v64, v65, v64, vcc
	v_div_scale_f32 v65, s[2:3], v64, v64, 1.0
	v_rcp_f32_e32 v66, v65
	s_nop 0
	v_fma_f32 v67, -v65, v66, 1.0
	v_fmac_f32_e32 v66, v67, v66
	v_div_scale_f32 v67, vcc, 1.0, v64, 1.0
	v_mul_f32_e32 v135, v67, v66
	v_fma_f32 v140, -v65, v135, v67
	v_fmac_f32_e32 v135, v140, v66
	v_fma_f32 v65, -v65, v135, v67
	v_div_fmas_f32 v65, v65, v66, v135
	v_div_fixup_f32 v140, v65, v64, 1.0
	v_pk_mul_f32 v[64:65], v[92:93], v[140:141] op_sel_hi:[1,0]
	v_pk_mul_f32 v[66:67], v[88:89], v[140:141] op_sel_hi:[1,0]
	v_pk_mul_f32 v[64:65], v[4:5], v[64:65]
	v_pk_mul_f32 v[66:67], v[6:7], v[66:67]
	global_store_dwordx4 v[130:131], v[64:67], off offset:-4096
	s_nop 1
	v_pk_mul_f32 v[64:65], v[94:95], v[140:141] op_sel_hi:[1,0]
	v_pk_mul_f32 v[66:67], v[90:91], v[140:141] op_sel_hi:[1,0]
	v_pk_mul_f32 v[64:65], v[0:1], v[64:65]
	v_pk_mul_f32 v[66:67], v[2:3], v[66:67]
	global_store_dwordx4 v[130:131], v[64:67], off offset:-4080
	s_waitcnt vmcnt(2)
	v_mov_b64_e32 v[90:91], v[54:55]
	v_mov_b64_e32 v[94:95], v[34:35]
	v_pk_mul_f32 v[64:65], v[80:81], v[140:141] op_sel_hi:[1,0]
	v_pk_mul_f32 v[66:67], v[84:85], v[140:141] op_sel_hi:[1,0]
	v_pk_mul_f32 v[64:65], v[12:13], v[64:65]
	v_pk_mul_f32 v[66:67], v[14:15], v[66:67]
	global_store_dwordx4 v[130:131], v[64:67], off offset:-2048
	v_mov_b64_e32 v[88:89], v[52:53]
	v_mov_b64_e32 v[92:93], v[32:33]
	v_pk_mul_f32 v[64:65], v[86:87], v[140:141] op_sel_hi:[1,0]
	v_pk_mul_f32 v[66:67], v[82:83], v[140:141] op_sel_hi:[1,0]
	v_pk_mul_f32 v[64:65], v[8:9], v[64:65]
	v_pk_mul_f32 v[66:67], v[10:11], v[66:67]
	global_store_dwordx4 v[130:131], v[64:67], off offset:-2032
	v_mov_b64_e32 v[82:83], v[50:51]
	v_mov_b64_e32 v[86:87], v[38:39]
	v_pk_mul_f32 v[64:65], v[76:77], v[140:141] op_sel_hi:[1,0]
	v_pk_mul_f32 v[66:67], v[72:73], v[140:141] op_sel_hi:[1,0]
	v_pk_mul_f32 v[64:65], v[20:21], v[64:65]
	v_pk_mul_f32 v[66:67], v[22:23], v[66:67]
	global_store_dwordx4 v[130:131], v[64:67], off
	v_mov_b64_e32 v[80:81], v[48:49]
	v_mov_b64_e32 v[84:85], v[36:37]
	v_pk_mul_f32 v[64:65], v[136:137], v[140:141] op_sel_hi:[1,0]
	v_pk_mul_f32 v[66:67], v[74:75], v[140:141] op_sel_hi:[1,0]
	v_pk_mul_f32 v[64:65], v[16:17], v[64:65]
	v_pk_mul_f32 v[66:67], v[18:19], v[66:67]
	global_store_dwordx4 v[130:131], v[64:67], off offset:16
	v_mov_b64_e32 v[74:75], v[62:63]
	v_mov_b64_e32 v[72:73], v[60:61]
	v_pk_mul_f32 v[64:65], v[78:79], v[140:141] op_sel_hi:[1,0]
	v_pk_mul_f32 v[66:67], v[68:69], v[140:141] op_sel_hi:[1,0]
	v_pk_mul_f32 v[64:65], v[28:29], v[64:65]
	v_pk_mul_f32 v[66:67], v[30:31], v[66:67]
	global_store_dwordx4 v[130:131], v[64:67], off offset:2048
	v_mov_b64_e32 v[78:79], v[42:43]
	v_mov_b64_e32 v[76:77], v[40:41]
	v_pk_mul_f32 v[64:65], v[138:139], v[140:141] op_sel_hi:[1,0]
	v_pk_mul_f32 v[66:67], v[70:71], v[140:141] op_sel_hi:[1,0]
	v_pk_mul_f32 v[64:65], v[24:25], v[64:65]
	v_pk_mul_f32 v[66:67], v[26:27], v[66:67]
	global_store_dwordx4 v[130:131], v[64:67], off offset:2064
	v_mov_b64_e32 v[70:71], v[46:47]
	v_lshl_add_u64 v[130:131], v[130:131], 0, s[4:5]
	v_mov_b64_e32 v[66:67], v[58:59]
	v_mov_b64_e32 v[64:65], v[56:57]
	v_mov_b64_e32 v[68:69], v[44:45]
	s_andn2_b64 exec, exec, s[6:7]
	s_cbranch_execz .LBB0_862
.LBB0_860:
	v_add_u32_e32 v96, s20, v96
	v_cmp_gt_i32_e32 vcc, s16, v96
	v_cmp_lt_i32_e64 s[0:1], s8, v96
	s_and_saveexec_b64 s[2:3], vcc
	s_cbranch_execz .Lfn_skip
	v_add_co_u32_e32 v44, vcc, 0xed58c000, v132
	s_nop 1
	v_addc_co_u32_e32 v45, vcc, -1, v133, vcc
	global_load_dwordx4 v[32:35], v[44:45], off offset:-3328 nt
	global_load_dwordx4 v[36:39], v[44:45], off offset:-2304 nt
	global_load_dwordx4 v[52:55], v[132:133], off nt
	global_load_dwordx4 v[48:51], v[132:133], off offset:1024 nt
	global_load_dwordx4 v[40:43], v[44:45], off offset:-1280 nt
	s_nop 0
	global_load_dwordx4 v[44:47], v[44:45], off offset:-256 nt
	s_nop 0
	global_load_dwordx4 v[60:63], v[132:133], off offset:2048 nt
	global_load_dwordx4 v[56:59], v[132:133], off offset:3072 nt
	s_waitcnt vmcnt(8)
	s_branch .LBB0_859
.Lfn_skip:
	s_waitcnt vmcnt(0)
	s_branch .LBB0_859
